# once-read f32 weight loads (phase-0 and filler conversion tiles, w_ada GEMV) marked nt so they do not displace GEMM tiles in L2
# speedup vs baseline: 1.0095x; 1.0095x over previous
; __device__ __forceinline__ void conv_tile(const Ctx& cx, const float* __restrict__ src, bfu* __restrict__ dst, int K, int N, int kt, int nt, int perm) {
;   char* smem = cx.lds;
;   float* tile = reinterpret_cast<float*>(smem);
;   const int tid = cx.tid;
;   const int k0 = kt * 64, n0 = nt * 64;
; #pragma unroll
;   for (int i = 0; i < 4; ++i) {
;     int kk = (tid >> 4) + 16 * i, nn = (tid & 15) * 4;
;     float4 v = *reinterpret_cast<const float4*>(src + (size_t)(k0 + kk) * N + n0 + nn);
;     tile[kk * 65 + nn] = v.x; tile[kk * 65 + nn + 1] = v.y; tile[kk * 65 + nn + 2] = v.z; tile[kk * 65 + nn + 3] = v.w;
;   }
;   __syncthreads();
; #pragma unroll
;   for (int i = 0; i < 2; ++i) {
;     int q = tid + 256 * i, nn = q >> 3, kc = q & 7;
;     int j = n0 + nn, drow = j;
;     if (perm == 1) {
;       if (j < DFF) drow = (j >> 4) * 32 + (j & 15);
;       else { int jj = j - DFF; drow = (jj >> 4) * 32 + 16 + (jj & 15); }
;     } else if (perm == 2) {
;       int sec = j >> 9;
;       if (sec == 5 || sec == 6 || sec == 9 || sec == 10) {
;         int d = j & 63;
;         int pos = d < 16 ? d : (d < 32 ? d + 16 : (d < 48 ? d - 16 : d));
;         drow = (j & ~63) + pos;
;       }
;     }
;     uint4 o;
;     o.x = pack2(tile[(kc * 8 + 0) * 65 + nn], tile[(kc * 8 + 1) * 65 + nn]);
;     o.y = pack2(tile[(kc * 8 + 2) * 65 + nn], tile[(kc * 8 + 3) * 65 + nn]);
;     o.z = pack2(tile[(kc * 8 + 4) * 65 + nn], tile[(kc * 8 + 5) * 65 + nn]);
;     o.w = pack2(tile[(kc * 8 + 6) * 65 + nn], tile[(kc * 8 + 7) * 65 + nn]);
;     *reinterpret_cast<uint4*>(dst + (size_t)drow * K + k0 + kc * 8) = o;
;   }
;   __syncthreads();
; }
.LBB0_33:
	s_or_b64 exec, exec, s[2:3]
	s_waitcnt lgkmcnt(0)
	s_barrier
	ds_read_b32 v0, v19
	s_movk_i32 s2, 0x18c0
	s_mov_b64 s[6:7], -1
	s_waitcnt lgkmcnt(0)
	v_add_u32_e32 v1, v0, v35
	v_cmp_gt_i32_e32 vcc, s2, v1
	s_and_saveexec_b64 s[2:3], vcc
	s_cbranch_execz .LBB0_28
	s_movk_i32 s6, 0x23f
	v_cmp_lt_i32_e32 vcc, s6, v1
	s_and_saveexec_b64 s[6:7], vcc
	s_xor_b64 s[6:7], exec, s[6:7]
	s_cbranch_execz .LBB0_47
	s_movk_i32 s10, 0x33f
	v_cmp_lt_u32_e32 vcc, s10, v1
	s_and_saveexec_b64 s[10:11], vcc
	s_xor_b64 s[10:11], exec, s[10:11]
	s_cbranch_execz .LBB0_45
	v_add_u16_e32 v0, 0xfcc0, v1
	v_mul_u32_u24_e32 v1, 0xbe83, v0
	v_lshrrev_b32_e32 v1, 23, v1
	v_mul_lo_u16_e32 v2, 0xac, v1
	v_sub_u16_e32 v5, v0, v2
	v_lshlrev_b16_e32 v0, 6, v1
	v_lshlrev_b16_e32 v4, 6, v5
	v_or_b32_e32 v1, v36, v0
	v_lshlrev_b32_e32 v2, 2, v4
	v_mov_b32_e32 v3, v18
	v_mul_u32_u24_e32 v6, 0xac00, v1
	v_or_b32_e32 v1, v39, v0
	v_lshl_add_u64 v[2:3], v[16:17], 0, v[2:3]
	v_mov_b32_e32 v7, v18
	v_mul_u32_u24_e32 v8, 0xac00, v1
	v_mov_b32_e32 v9, v18
	v_lshl_add_u64 v[6:7], v[2:3], 0, v[6:7]
	v_lshl_add_u64 v[10:11], v[2:3], 0, v[8:9]
	global_load_dwordx4 v[6:9], v[6:7], off nt
	s_nop 0
	global_load_dwordx4 v[10:13], v[10:11], off nt
	v_or_b32_e32 v1, v41, v0
	v_mul_u32_u24_e32 v14, 0xac00, v1
	v_mov_b32_e32 v15, v18
	v_lshl_add_u64 v[14:15], v[2:3], 0, v[14:15]
	v_or_b32_e32 v1, v43, v0
	global_load_dwordx4 v[20:23], v[14:15], off nt
	v_mul_u32_u24_e32 v14, 0xac00, v1
	v_mov_b32_e32 v15, v18
	v_lshl_add_u64 v[2:3], v[2:3], 0, v[14:15]
	global_load_dwordx4 v[26:29], v[2:3], off nt
	s_movk_i32 s12, 0x55
	v_or_b32_e32 v1, v45, v4
	v_cmp_lt_u16_e32 vcc, s12, v5
	v_lshlrev_b32_e32 v1, 1, v1
	s_waitcnt vmcnt(3)
	ds_write2_b32 v38, v6, v7 offset1:1
	ds_write2_b32 v38, v8, v9 offset0:2 offset1:3
	s_waitcnt vmcnt(2)
	ds_write2_b32 v40, v10, v11 offset1:1
	ds_write2_b32 v40, v12, v13 offset0:2 offset1:3
	s_waitcnt vmcnt(1)
	ds_write2_b32 v42, v20, v21 offset1:1
	ds_write2_b32 v42, v22, v23 offset0:2 offset1:3
	s_waitcnt vmcnt(0)
	ds_write2_b32 v44, v26, v27 offset1:1
	ds_write2_b32 v44, v28, v29 offset0:2 offset1:3
	s_waitcnt lgkmcnt(0)
	s_barrier
	s_and_saveexec_b64 s[12:13], vcc
	s_xor_b64 s[12:13], exec, s[12:13]
	v_add_u32_e32 v1, 0x7fffd500, v1
	s_mov_b32 s14, 0x7fffffa0
	v_and_or_b32 v2, v1, s14, v50
	s_andn2_saveexec_b64 s[12:13], s[12:13]
	s_movk_i32 s14, 0x3fa0
	v_and_or_b32 v2, v1, s14, v46
	s_or_b64 exec, exec, s[12:13]
	v_add_u32_e32 v5, 0x400, v47
	ds_read2_b32 v[6:7], v47 offset1:65
	ds_read2_b32 v[8:9], v47 offset0:130 offset1:195
	ds_read2_b32 v[10:11], v5 offset0:4 offset1:69
	ds_read2_b32 v[12:13], v5 offset0:134 offset1:199
	v_lshlrev_b32_e32 v0, 1, v0
	v_mov_b32_e32 v1, v18
	v_mov_b32_e32 v3, v18
	v_lshl_add_u64 v[0:1], v[24:25], 0, v[0:1]
	v_lshlrev_b64 v[2:3], 12, v[2:3]
	s_waitcnt lgkmcnt(3)
	v_cvt_pk_bf16_f32 v6, v6, v7
	s_waitcnt lgkmcnt(2)
	v_cvt_pk_bf16_f32 v7, v8, v9
	s_waitcnt lgkmcnt(1)
	v_cvt_pk_bf16_f32 v8, v10, v11
	s_waitcnt lgkmcnt(0)
	v_cvt_pk_bf16_f32 v9, v12, v13
	v_lshl_add_u64 v[2:3], v[0:1], 0, v[2:3]
	global_store_dwordx4 v[2:3], v[6:9], off
	v_or_b32_e32 v2, v48, v4
	v_lshlrev_b32_e32 v3, 1, v2
	s_and_saveexec_b64 s[12:13], vcc
	s_xor_b64 s[12:13], exec, s[12:13]
	v_add_u32_e32 v2, 0x7fffd500, v3
	s_mov_b32 s14, 0x7fffffe0
	v_and_or_b32 v2, v2, s14, v50
	s_andn2_saveexec_b64 s[12:13], s[12:13]
	s_movk_i32 s14, 0x3fe0
	v_and_or_b32 v2, v3, s14, v46
	s_or_b64 exec, exec, s[12:13]
	ds_read2_b32 v[6:7], v47 offset0:32 offset1:97
	ds_read2_b32 v[8:9], v47 offset0:162 offset1:227
	ds_read2_b32 v[10:11], v5 offset0:36 offset1:101
	ds_read2_b32 v[12:13], v5 offset0:166 offset1:231
	v_mov_b32_e32 v3, v18
	v_lshlrev_b64 v[2:3], 12, v[2:3]
	s_waitcnt lgkmcnt(3)
	v_cvt_pk_bf16_f32 v4, v6, v7
	s_waitcnt lgkmcnt(2)
	v_cvt_pk_bf16_f32 v5, v8, v9
	s_waitcnt lgkmcnt(1)
	v_cvt_pk_bf16_f32 v6, v10, v11
	s_waitcnt lgkmcnt(0)
	v_cvt_pk_bf16_f32 v7, v12, v13
	v_lshl_add_u64 v[0:1], v[0:1], 0, v[2:3]
	global_store_dwordx4 v[0:1], v[4:7], off
	s_barrier

; __device__ __forceinline__ void phase0(const Ctx& cx, const Params& p) {
;     ...
;       const float* wp = p.w_ada + ((size_t)l * DM + ks * KC) * NMOD + col;
; #pragma unroll 4
;       for (int k = 0; k < KC; ++k) {
;         float4 w = *reinterpret_cast<const float4*>(wp + (size_t)k * NMOD);
; #pragma unroll
;         for (int v = 0; v < 5; ++v) {
;           float s = cs[v * KC + k];
;           acc[v].x += s * w.x; acc[v].y += s * w.y; acc[v].z += s * w.z; acc[v].w += s * w.w;
;         }
;       }
;       float* mp = reinterpret_cast<float*>(p.ws + OFF_MODP);
; #pragma unroll
;       for (int v = 0; v < 5; ++v) *reinterpret_cast<float4*>(mp + ((size_t)(l * KS_MOD + ks) * 5 + v) * NMOD + col) = acc[v];
.LBB0_51:
	v_lshl_add_u64 v[58:59], v[30:31], 0, s[10:11]
	v_add_co_u32_e32 v60, vcc, s33, v58
	s_mov_b32 s12, 0x24000
	s_nop 0
	v_addc_co_u32_e32 v61, vcc, 0, v59, vcc
	v_add_co_u32_e32 v62, vcc, s12, v58
	global_load_dwordx4 v[54:57], v[58:59], off nt
	s_nop 0
	v_addc_co_u32_e32 v63, vcc, 0, v59, vcc
	s_mov_b32 s12, 0x36000
	v_add_co_u32_e32 v66, vcc, s12, v58
	s_add_u32 s10, s10, 0x48000
	s_nop 0
	v_addc_co_u32_e32 v67, vcc, 0, v59, vcc
	global_load_dwordx4 v[58:61], v[60:61], off nt
	s_nop 0
	global_load_dwordx4 v[62:65], v[62:63], off nt
	s_nop 0
	global_load_dwordx4 v[66:69], v[66:67], off nt
	ds_read_b128 v[70:73], v27
	ds_read_b128 v[74:77], v27 offset:512
	ds_read_b128 v[78:81], v27 offset:1024
	ds_read_b128 v[82:85], v27 offset:1536
	ds_read_b128 v[86:89], v27 offset:2048
	s_addc_u32 s11, s11, 0
	s_waitcnt lgkmcnt(4)
	v_mov_b32_e32 v90, v73
	s_waitcnt lgkmcnt(3)
	v_mov_b32_e32 v92, v77
	s_waitcnt lgkmcnt(2)
	v_mov_b32_e32 v94, v81
	s_waitcnt lgkmcnt(1)
	v_mov_b32_e32 v96, v85
	s_waitcnt lgkmcnt(0)
	v_mov_b32_e32 v98, v89
	v_add_u32_e32 v27, 16, v27
	s_cmp_eq_u32 s10, 0x900000
	s_waitcnt vmcnt(3)
	v_pk_fma_f32 v[20:21], v[54:55], v[70:71], v[20:21] op_sel_hi:[1,0,1]
	v_pk_fma_f32 v[22:23], v[56:57], v[70:71], v[22:23] op_sel_hi:[1,0,1]
	v_pk_fma_f32 v[12:13], v[54:55], v[74:75], v[12:13] op_sel_hi:[1,0,1]
	v_pk_fma_f32 v[14:15], v[56:57], v[74:75], v[14:15] op_sel_hi:[1,0,1]
	v_pk_fma_f32 v[8:9], v[54:55], v[78:79], v[8:9] op_sel_hi:[1,0,1]
	v_pk_fma_f32 v[10:11], v[56:57], v[78:79], v[10:11] op_sel_hi:[1,0,1]
	v_pk_fma_f32 v[4:5], v[54:55], v[82:83], v[4:5] op_sel_hi:[1,0,1]
	v_pk_fma_f32 v[6:7], v[56:57], v[82:83], v[6:7] op_sel_hi:[1,0,1]
	v_pk_fma_f32 v[0:1], v[54:55], v[86:87], v[0:1] op_sel_hi:[1,0,1]
	v_pk_fma_f32 v[2:3], v[56:57], v[86:87], v[2:3] op_sel_hi:[1,0,1]
	s_waitcnt vmcnt(2)
	v_pk_fma_f32 v[20:21], v[58:59], v[70:71], v[20:21] op_sel:[0,1,0]
	v_pk_fma_f32 v[22:23], v[60:61], v[70:71], v[22:23] op_sel:[0,1,0]
	v_pk_fma_f32 v[12:13], v[58:59], v[74:75], v[12:13] op_sel:[0,1,0]
	v_pk_fma_f32 v[14:15], v[60:61], v[74:75], v[14:15] op_sel:[0,1,0]
	v_pk_fma_f32 v[8:9], v[58:59], v[78:79], v[8:9] op_sel:[0,1,0]
	v_pk_fma_f32 v[10:11], v[60:61], v[78:79], v[10:11] op_sel:[0,1,0]
	v_pk_fma_f32 v[4:5], v[58:59], v[82:83], v[4:5] op_sel:[0,1,0]
	v_pk_fma_f32 v[6:7], v[60:61], v[82:83], v[6:7] op_sel:[0,1,0]
	v_pk_fma_f32 v[0:1], v[58:59], v[86:87], v[0:1] op_sel:[0,1,0]
	v_pk_fma_f32 v[2:3], v[60:61], v[86:87], v[2:3] op_sel:[0,1,0]
	s_waitcnt vmcnt(1)
	v_pk_fma_f32 v[20:21], v[62:63], v[72:73], v[20:21] op_sel_hi:[1,0,1]
	v_pk_fma_f32 v[22:23], v[64:65], v[72:73], v[22:23] op_sel_hi:[1,0,1]
	v_pk_fma_f32 v[12:13], v[62:63], v[76:77], v[12:13] op_sel_hi:[1,0,1]
	v_pk_fma_f32 v[14:15], v[64:65], v[76:77], v[14:15] op_sel_hi:[1,0,1]
	v_pk_fma_f32 v[8:9], v[62:63], v[80:81], v[8:9] op_sel_hi:[1,0,1]
	v_pk_fma_f32 v[10:11], v[64:65], v[80:81], v[10:11] op_sel_hi:[1,0,1]
	v_pk_fma_f32 v[4:5], v[62:63], v[84:85], v[4:5] op_sel_hi:[1,0,1]
	v_pk_fma_f32 v[6:7], v[64:65], v[84:85], v[6:7] op_sel_hi:[1,0,1]
	v_pk_fma_f32 v[0:1], v[62:63], v[88:89], v[0:1] op_sel_hi:[1,0,1]
	v_pk_fma_f32 v[2:3], v[64:65], v[88:89], v[2:3] op_sel_hi:[1,0,1]
	s_waitcnt vmcnt(0)
	v_pk_fma_f32 v[20:21], v[66:67], v[90:91], v[20:21] op_sel_hi:[1,0,1]
	v_pk_fma_f32 v[22:23], v[68:69], v[90:91], v[22:23] op_sel_hi:[1,0,1]
	v_pk_fma_f32 v[12:13], v[66:67], v[92:93], v[12:13] op_sel_hi:[1,0,1]
	v_pk_fma_f32 v[14:15], v[68:69], v[92:93], v[14:15] op_sel_hi:[1,0,1]
	v_pk_fma_f32 v[8:9], v[66:67], v[94:95], v[8:9] op_sel_hi:[1,0,1]
	v_pk_fma_f32 v[10:11], v[68:69], v[94:95], v[10:11] op_sel_hi:[1,0,1]
	v_pk_fma_f32 v[4:5], v[66:67], v[96:97], v[4:5] op_sel_hi:[1,0,1]
	v_pk_fma_f32 v[6:7], v[68:69], v[96:97], v[6:7] op_sel_hi:[1,0,1]
	v_pk_fma_f32 v[0:1], v[66:67], v[98:99], v[0:1] op_sel_hi:[1,0,1]
	v_pk_fma_f32 v[2:3], v[68:69], v[98:99], v[2:3] op_sel_hi:[1,0,1]
	s_cbranch_scc0 .LBB0_51
	v_lshl_add_u32 v26, v26, 4, v52
	v_lshl_add_u32 v30, v26, 2, v26
	v_lshl_add_u64 v[26:27], v[28:29], 2, s[26:27]
	v_mad_i64_i32 v[26:27], s[10:11], v30, s33, v[26:27]
	global_store_dwordx4 v[26:27], v[20:23], off
	s_nop 1
	v_add_co_u32_e32 v20, vcc, 0x12000, v26
	s_nop 1
	v_addc_co_u32_e32 v21, vcc, 0, v27, vcc
	global_store_dwordx4 v[20:21], v[12:15], off
	s_nop 1
	v_add_co_u32_e32 v12, vcc, 0x24000, v26
	s_nop 1
	v_addc_co_u32_e32 v13, vcc, 0, v27, vcc
	global_store_dwordx4 v[12:13], v[8:11], off
	s_nop 1
	v_add_co_u32_e32 v8, vcc, 0x36000, v26
	s_nop 1
	v_addc_co_u32_e32 v9, vcc, 0, v27, vcc
	global_store_dwordx4 v[8:9], v[4:7], off
	s_nop 1
	v_add_co_u32_e32 v4, vcc, 0x48000, v26
	s_nop 1
	v_addc_co_u32_e32 v5, vcc, 0, v27, vcc
	global_store_dwordx4 v[4:5], v[0:3], off
	s_barrier
	s_branch .LBB0_27

; __device__ __forceinline__ void conv_tile(const Ctx& cx, const float* __restrict__ src, bfu* __restrict__ dst, int K, int N, int kt, int nt, int perm) {
;   char* smem = cx.lds;
;   float* tile = reinterpret_cast<float*>(smem);
;   const int tid = cx.tid;
;   const int k0 = kt * 64, n0 = nt * 64;
; #pragma unroll
;   for (int i = 0; i < 4; ++i) {
;     int kk = (tid >> 4) + 16 * i, nn = (tid & 15) * 4;
;     float4 v = *reinterpret_cast<const float4*>(src + (size_t)(k0 + kk) * N + n0 + nn);
;     tile[kk * 65 + nn] = v.x; tile[kk * 65 + nn + 1] = v.y; tile[kk * 65 + nn + 2] = v.z; tile[kk * 65 + nn + 3] = v.w;
;   }
;   __syncthreads();
; #pragma unroll
;   for (int i = 0; i < 2; ++i) {
;     int q = tid + 256 * i, nn = q >> 3, kc = q & 7;
;     int j = n0 + nn, drow = j;
;     if (perm == 1) {
;       if (j < DFF) drow = (j >> 4) * 32 + (j & 15);
;       else { int jj = j - DFF; drow = (jj >> 4) * 32 + 16 + (jj & 15); }
;     } else if (perm == 2) {
;       int sec = j >> 9;
;       if (sec == 5 || sec == 6 || sec == 9 || sec == 10) {
;         int d = j & 63;
;         int pos = d < 16 ? d : (d < 32 ? d + 16 : (d < 48 ? d - 16 : d));
;         drow = (j & ~63) + pos;
;       }
;     }
;     uint4 o;
;     o.x = pack2(tile[(kc * 8 + 0) * 65 + nn], tile[(kc * 8 + 1) * 65 + nn]);
;     o.y = pack2(tile[(kc * 8 + 2) * 65 + nn], tile[(kc * 8 + 3) * 65 + nn]);
;     o.z = pack2(tile[(kc * 8 + 4) * 65 + nn], tile[(kc * 8 + 5) * 65 + nn]);
;     o.w = pack2(tile[(kc * 8 + 6) * 65 + nn], tile[(kc * 8 + 7) * 65 + nn]);
;     *reinterpret_cast<uint4*>(dst + (size_t)drow * K + k0 + kc * 8) = o;
;   }
;   __syncthreads();
; }
; __device__ __forceinline__ void conv_item(const Ctx& cx, const Params& p, int l, int r) {
;     ...
;   } else if (r < 20096) {
;     r -= 16512;
;     conv_tile(cx, p.w_in + (size_t)l * 2048 * 7168, reinterpret_cast<bfu*>(p.ws + OFF_WIN) + (size_t)l * 7168 * 2048, 2048, 7168, r / 112, r % 112, 2);
;   } else {
;     r -= 20096;
;     conv_tile(cx, p.w_out + (size_t)l * 2048 * 2048, reinterpret_cast<bfu*>(p.ws + OFF_WOUT) + (size_t)l * 2048 * 2048, 2048, 2048, r / 32, r % 32, 0);
;   }
.LBB0_928:
	s_or_b64 exec, exec, s[0:1]
	v_add_u32_e32 v5, v6, v5
	s_movk_i32 s0, 0x2aff
	v_cmp_lt_i32_e32 vcc, s0, v5
	s_and_saveexec_b64 s[0:1], vcc
	s_xor_b64 s[10:11], exec, s[0:1]
	s_cbranch_execz .LBB0_946
	s_movk_i32 s0, 0x407f
	v_cmp_lt_u32_e32 vcc, s0, v5
	s_and_saveexec_b64 s[0:1], vcc
	s_xor_b64 s[2:3], exec, s[0:1]
	s_cbranch_execz .LBB0_943
	s_movk_i32 s0, 0x4e7f
	v_cmp_lt_u32_e32 vcc, s0, v5
	s_and_saveexec_b64 s[0:1], vcc
	s_xor_b64 s[0:1], exec, s[0:1]
	s_cbranch_execz .LBB0_932
	v_lshlrev_b32_e32 v6, 24, v4
	v_lshlrev_b32_e32 v8, 23, v4
	v_lshlrev_b32_e32 v4, 1, v5
	v_and_b32_e32 v4, 0x7fffffc0, v4
	v_readlane_b32 s72, v254, 9
	v_add_u32_e32 v24, 0xffff6300, v4
	v_lshlrev_b32_e32 v4, 6, v5
	v_mov_b32_e32 v7, v18
	v_readlane_b32 s78, v254, 15
	v_readlane_b32 s79, v254, 16
	v_and_b32_e32 v42, 0x7c0, v4
	v_lshlrev_b32_e32 v4, 2, v42
	v_lshl_add_u64 v[6:7], s[78:79], 0, v[6:7]
	v_mov_b32_e32 v5, v18
	v_lshl_add_u64 v[4:5], v[6:7], 0, v[4:5]
	v_lshlrev_b32_e32 v6, 2, v0
	v_mov_b32_e32 v7, v18
	v_lshl_add_u64 v[26:27], v[4:5], 0, v[6:7]
	v_or_b32_e32 v4, v24, v1
	v_mov_b32_e32 v5, v18
	v_lshlrev_b64 v[4:5], 13, v[4:5]
	v_lshl_add_u64 v[4:5], v[26:27], 0, v[4:5]
	global_load_dwordx4 v[4:7], v[4:5], off nt
	v_readlane_b32 s12, v252, 14
	v_mov_b32_e32 v9, v18
	v_readlane_b32 s13, v252, 15
	v_mov_b32_e32 v25, v18
	v_or_b32_e32 v40, v42, v16
	v_lshl_add_u64 v[8:9], s[12:13], 0, v[8:9]
	v_lshlrev_b32_e32 v40, 12, v40
	v_mov_b32_e32 v41, v18
	v_readlane_b32 s73, v254, 10
	v_readlane_b32 s74, v254, 11
	v_readlane_b32 s75, v254, 12
	v_readlane_b32 s76, v254, 13
	v_readlane_b32 s77, v254, 14
	v_readlane_b32 s80, v254, 17
	v_readlane_b32 s81, v254, 18
	v_readlane_b32 s82, v254, 19
	v_readlane_b32 s83, v254, 20
	v_readlane_b32 s84, v254, 21
	v_readlane_b32 s85, v254, 22
	v_readlane_b32 s86, v254, 23
	v_readlane_b32 s87, v254, 24
	s_waitcnt vmcnt(0)
	ds_write2_b32 v3, v4, v5 offset1:1
	ds_write2_b32 v3, v6, v7 offset0:2 offset1:3
	v_or_b32_e32 v4, v24, v10
	v_mov_b32_e32 v5, v18
	v_lshlrev_b64 v[4:5], 13, v[4:5]
	v_lshl_add_u64 v[4:5], v[26:27], 0, v[4:5]
	global_load_dwordx4 v[4:7], v[4:5], off nt
	s_waitcnt vmcnt(0)
	ds_write2_b32 v11, v4, v5 offset1:1
	ds_write2_b32 v11, v6, v7 offset0:2 offset1:3
	v_or_b32_e32 v4, v24, v12
	v_mov_b32_e32 v5, v18
	v_lshlrev_b64 v[4:5], 13, v[4:5]
	v_lshl_add_u64 v[4:5], v[26:27], 0, v[4:5]
	global_load_dwordx4 v[4:7], v[4:5], off nt
	s_waitcnt vmcnt(0)
	ds_write2_b32 v13, v4, v5 offset1:1
	ds_write2_b32 v13, v6, v7 offset0:2 offset1:3
	v_or_b32_e32 v4, v24, v14
	v_mov_b32_e32 v5, v18
	v_lshlrev_b64 v[4:5], 13, v[4:5]
	v_lshl_add_u64 v[4:5], v[26:27], 0, v[4:5]
	global_load_dwordx4 v[4:7], v[4:5], off nt
	s_waitcnt vmcnt(0)
	ds_write2_b32 v15, v4, v5 offset1:1
	ds_write2_b32 v15, v6, v7 offset0:2 offset1:3
	v_lshl_add_u64 v[4:5], v[24:25], 1, v[8:9]
	v_lshlrev_b32_e32 v6, 1, v2
	v_mov_b32_e32 v7, v18
	v_lshl_add_u64 v[8:9], v[4:5], 0, v[6:7]
	v_add_u32_e32 v7, 0x400, v17
	s_waitcnt lgkmcnt(0)
	s_barrier
	ds_read2_b32 v[24:25], v17 offset1:32
	ds_read2_b32 v[26:27], v17 offset0:65 offset1:97
	ds_read2_b32 v[28:29], v17 offset0:130 offset1:162
	ds_read2_b32 v[30:31], v17 offset0:195 offset1:227
	ds_read2_b32 v[32:33], v7 offset0:4 offset1:36
	ds_read2_b32 v[34:35], v7 offset0:69 offset1:101
	ds_read2_b32 v[36:37], v7 offset0:134 offset1:166
	ds_read2_b32 v[38:39], v7 offset0:199 offset1:231
	v_lshl_add_u64 v[40:41], v[8:9], 0, v[40:41]
	s_waitcnt lgkmcnt(6)
	v_cvt_pk_bf16_f32 v4, v24, v26
	s_waitcnt lgkmcnt(4)
	v_cvt_pk_bf16_f32 v5, v28, v30
	s_waitcnt lgkmcnt(2)
	v_cvt_pk_bf16_f32 v6, v32, v34
	s_waitcnt lgkmcnt(0)
	v_cvt_pk_bf16_f32 v7, v36, v38
	v_or_b32_e32 v24, v42, v19
	global_store_dwordx4 v[40:41], v[4:7], off
	v_lshlrev_b32_e32 v24, 12, v24
	s_nop 0
	v_cvt_pk_bf16_f32 v4, v25, v27
	v_mov_b32_e32 v25, v18
	v_cvt_pk_bf16_f32 v5, v29, v31
	v_cvt_pk_bf16_f32 v6, v33, v35
	v_cvt_pk_bf16_f32 v7, v37, v39
	v_lshl_add_u64 v[8:9], v[8:9], 0, v[24:25]
	global_store_dwordx4 v[8:9], v[4:7], off
	s_barrier
.LBB0_932:
	s_andn2_saveexec_b64 s[12:13], s[0:1]
	s_cbranch_execz .LBB0_942
	s_mov_b32 s0, 0x3800000
	v_readlane_b32 s72, v254, 9
	v_mul_lo_u32 v6, v4, s0
	v_mov_b32_e32 v7, v18
	v_readlane_b32 s76, v254, 13
	v_readlane_b32 s77, v254, 14
	v_add_u16_e32 v5, 0xbf80, v5
	s_movk_i32 s0, 0x70
	v_lshl_add_u64 v[8:9], s[76:77], 0, v[6:7]
	v_lshrrev_b16_e32 v6, 4, v5
	v_mul_u32_u24_e32 v6, 0x2493, v6
	v_mul_lo_u16_sdwa v7, v6, s0 dst_sel:DWORD dst_unused:UNUSED_PAD src0_sel:WORD_1 src1_sel:DWORD
	v_sub_u16_e32 v7, v5, v7
	v_lshlrev_b16_sdwa v5, v191, v6 dst_sel:DWORD dst_unused:UNUSED_PAD src0_sel:DWORD src1_sel:WORD_1
	v_lshlrev_b16_e32 v6, 6, v7
	v_lshlrev_b32_e32 v24, 2, v6
	v_mov_b32_e32 v25, v18
	v_lshl_add_u64 v[8:9], v[8:9], 0, v[24:25]
	v_lshlrev_b32_e32 v24, 2, v0
	v_or_b32_e32 v7, v1, v5
	v_lshl_add_u64 v[8:9], v[8:9], 0, v[24:25]
	v_mul_u32_u24_e32 v24, 0x7000, v7
	v_lshl_add_u64 v[24:25], v[8:9], 0, v[24:25]
	global_load_dwordx4 v[24:27], v[24:25], off nt
	v_or_b32_e32 v7, v10, v5
	s_mov_b64 s[14:15], 0
	v_readlane_b32 s73, v254, 10
	v_readlane_b32 s74, v254, 11
	v_readlane_b32 s75, v254, 12
	v_readlane_b32 s78, v254, 15
	v_readlane_b32 s79, v254, 16
	v_readlane_b32 s80, v254, 17
	v_readlane_b32 s81, v254, 18
	v_readlane_b32 s82, v254, 19
	v_readlane_b32 s83, v254, 20
	v_readlane_b32 s84, v254, 21
	v_readlane_b32 s85, v254, 22
	v_readlane_b32 s86, v254, 23
	v_readlane_b32 s87, v254, 24
	s_waitcnt vmcnt(0)
	ds_write2_b32 v3, v24, v25 offset1:1
	ds_write2_b32 v3, v26, v27 offset0:2 offset1:3
	v_mul_u32_u24_e32 v24, 0x7000, v7
	v_mov_b32_e32 v25, v18
	v_lshl_add_u64 v[24:25], v[8:9], 0, v[24:25]
	global_load_dwordx4 v[24:27], v[24:25], off nt
	v_or_b32_e32 v7, v12, v5
	s_waitcnt vmcnt(0)
	ds_write2_b32 v11, v24, v25 offset1:1
	ds_write2_b32 v11, v26, v27 offset0:2 offset1:3
	v_mul_u32_u24_e32 v24, 0x7000, v7
	v_mov_b32_e32 v25, v18
	v_lshl_add_u64 v[24:25], v[8:9], 0, v[24:25]
	global_load_dwordx4 v[24:27], v[24:25], off nt
	v_or_b32_e32 v7, v14, v5
	s_waitcnt vmcnt(0)
	ds_write2_b32 v13, v24, v25 offset1:1
	ds_write2_b32 v13, v26, v27 offset0:2 offset1:3
	v_mul_u32_u24_e32 v24, 0x7000, v7
	v_mov_b32_e32 v25, v18
	v_lshl_add_u64 v[8:9], v[8:9], 0, v[24:25]
	global_load_dwordx4 v[24:27], v[8:9], off nt
	v_lshrrev_b32_e32 v7, 9, v6
	v_cmp_lt_i32_e64 s[0:1], 8, v7
	v_cmp_gt_i32_e32 vcc, 11, v7
	s_waitcnt vmcnt(0)
	ds_write2_b32 v15, v24, v25 offset1:1
	ds_write2_b32 v15, v26, v27 offset0:2 offset1:3
	s_waitcnt lgkmcnt(0)
	s_barrier
	s_and_saveexec_b64 s[16:17], s[0:1]
	s_xor_b64 s[0:1], exec, s[16:17]
	s_cbranch_execz .LBB0_955
	s_and_b64 s[14:15], vcc, exec
	s_or_saveexec_b64 s[16:17], s[0:1]
	v_add_u32_e32 v8, -5, v7
	s_xor_b64 exec, exec, s[16:17]
	s_cbranch_execnz .LBB0_956

; __device__ __forceinline__ void conv_tile(const Ctx& cx, const float* __restrict__ src, bfu* __restrict__ dst, int K, int N, int kt, int nt, int perm) {
;   char* smem = cx.lds;
;   float* tile = reinterpret_cast<float*>(smem);
;   const int tid = cx.tid;
;   const int k0 = kt * 64, n0 = nt * 64;
; #pragma unroll
;   for (int i = 0; i < 4; ++i) {
;     int kk = (tid >> 4) + 16 * i, nn = (tid & 15) * 4;
;     float4 v = *reinterpret_cast<const float4*>(src + (size_t)(k0 + kk) * N + n0 + nn);
;     tile[kk * 65 + nn] = v.x; tile[kk * 65 + nn + 1] = v.y; tile[kk * 65 + nn + 2] = v.z; tile[kk * 65 + nn + 3] = v.w;
;   }
;   __syncthreads();
; #pragma unroll
;   for (int i = 0; i < 2; ++i) {
;     int q = tid + 256 * i, nn = q >> 3, kc = q & 7;
;     int j = n0 + nn, drow = j;
;     if (perm == 1) {
;       if (j < DFF) drow = (j >> 4) * 32 + (j & 15);
;       else { int jj = j - DFF; drow = (jj >> 4) * 32 + 16 + (jj & 15); }
;     } else if (perm == 2) {
;       int sec = j >> 9;
;       if (sec == 5 || sec == 6 || sec == 9 || sec == 10) {
;         int d = j & 63;
;         int pos = d < 16 ? d : (d < 32 ? d + 16 : (d < 48 ? d - 16 : d));
;         drow = (j & ~63) + pos;
;       }
;     }
;     uint4 o;
;     o.x = pack2(tile[(kc * 8 + 0) * 65 + nn], tile[(kc * 8 + 1) * 65 + nn]);
;     o.y = pack2(tile[(kc * 8 + 2) * 65 + nn], tile[(kc * 8 + 3) * 65 + nn]);
;     o.z = pack2(tile[(kc * 8 + 4) * 65 + nn], tile[(kc * 8 + 5) * 65 + nn]);
;     o.w = pack2(tile[(kc * 8 + 6) * 65 + nn], tile[(kc * 8 + 7) * 65 + nn]);
;     *reinterpret_cast<uint4*>(dst + (size_t)drow * K + k0 + kc * 8) = o;
;   }
;   __syncthreads();
; }
; __device__ __forceinline__ void conv_item(const Ctx& cx, const Params& p, int l, int r) {
;     ...
;   } else if (r < 16512) {
;     r -= 11008;
;     int f = r / 2752, rr = r % 2752;
;     conv_tile(cx, p.ffn_w_out + (size_t)(l * 2 + f) * 5504 * 2048, reinterpret_cast<bfu*>(p.ws + OFF_WFOUT) + (size_t)(l * 2 + f) * 2048 * 5504,
;               5504, 2048, rr / 32, rr % 32, 0);
.LBB0_943:
	s_andn2_saveexec_b64 s[0:1], s[2:3]
	s_cbranch_execz .LBB0_945
	v_add_u32_e32 v6, 0xffffd500, v5
	v_cmp_lt_u32_e32 vcc, s20, v6
	s_movk_i32 s2, 0xac0
	v_add_u32_e32 v5, 0xffffca40, v5
	v_cndmask_b32_e64 v7, 0, 1, vcc
	v_cmp_gt_u32_e32 vcc, s2, v6
	s_mov_b32 s2, 0x1580000
	v_readlane_b32 s72, v254, 9
	v_cndmask_b32_e32 v24, v5, v6, vcc
	v_lshl_or_b32 v6, v4, 1, v7
	v_mul_lo_u32 v4, v6, s21
	v_mul_lo_u32 v6, v6, s2
	v_mov_b32_e32 v7, v18
	v_lshl_add_u64 v[8:9], s[44:45], 0, v[6:7]
	v_lshlrev_b32_e32 v6, 1, v24
	v_and_b32_e32 v26, 0x7fffffc0, v6
	v_lshlrev_b32_e32 v6, 6, v24
	v_mov_b32_e32 v5, v18
	v_readlane_b32 s74, v254, 11
	v_readlane_b32 s75, v254, 12
	v_and_b32_e32 v42, 0x7c0, v6
	v_lshlrev_b32_e32 v6, 2, v42
	v_lshl_add_u64 v[4:5], s[74:75], 0, v[4:5]
	v_lshl_add_u64 v[4:5], v[4:5], 0, v[6:7]
	v_lshlrev_b32_e32 v6, 2, v0
	v_lshl_add_u64 v[24:25], v[4:5], 0, v[6:7]
	v_or_b32_e32 v4, v26, v1
	v_mov_b32_e32 v5, v18
	v_lshlrev_b64 v[4:5], 13, v[4:5]
	v_lshl_add_u64 v[4:5], v[24:25], 0, v[4:5]
	global_load_dwordx4 v[4:7], v[4:5], off nt
	v_or_b32_e32 v40, v42, v16
	v_mul_u32_u24_e32 v40, 0x2b00, v40
	v_mov_b32_e32 v41, v18
	v_readlane_b32 s73, v254, 10
	v_readlane_b32 s76, v254, 13
	v_readlane_b32 s77, v254, 14
	v_readlane_b32 s78, v254, 15
	v_readlane_b32 s79, v254, 16
	v_readlane_b32 s80, v254, 17
	v_readlane_b32 s81, v254, 18
	v_readlane_b32 s82, v254, 19
	v_readlane_b32 s83, v254, 20
	v_readlane_b32 s84, v254, 21
	v_readlane_b32 s85, v254, 22
	v_readlane_b32 s86, v254, 23
	v_readlane_b32 s87, v254, 24
	s_waitcnt vmcnt(0)
	ds_write2_b32 v3, v4, v5 offset1:1
	ds_write2_b32 v3, v6, v7 offset0:2 offset1:3
	v_or_b32_e32 v4, v26, v10
	v_mov_b32_e32 v5, v18
	v_lshlrev_b64 v[4:5], 13, v[4:5]
	v_lshl_add_u64 v[4:5], v[24:25], 0, v[4:5]
	global_load_dwordx4 v[4:7], v[4:5], off nt
	s_waitcnt vmcnt(0)
	ds_write2_b32 v11, v4, v5 offset1:1
	ds_write2_b32 v11, v6, v7 offset0:2 offset1:3
	v_or_b32_e32 v4, v26, v12
	v_mov_b32_e32 v5, v18
	v_lshlrev_b64 v[4:5], 13, v[4:5]
	v_lshl_add_u64 v[4:5], v[24:25], 0, v[4:5]
	global_load_dwordx4 v[4:7], v[4:5], off nt
	s_waitcnt vmcnt(0)
	ds_write2_b32 v13, v4, v5 offset1:1
	ds_write2_b32 v13, v6, v7 offset0:2 offset1:3
	v_or_b32_e32 v4, v26, v14
	v_mov_b32_e32 v5, v18
	v_lshlrev_b64 v[4:5], 13, v[4:5]
	v_lshl_add_u64 v[4:5], v[24:25], 0, v[4:5]
	global_load_dwordx4 v[4:7], v[4:5], off nt
	s_waitcnt vmcnt(0)
	ds_write2_b32 v15, v4, v5 offset1:1
	ds_write2_b32 v15, v6, v7 offset0:2 offset1:3
	v_lshlrev_b32_e32 v4, 1, v26
	v_mov_b32_e32 v5, v18
	v_lshl_add_u64 v[4:5], v[8:9], 0, v[4:5]
	v_lshlrev_b32_e32 v6, 1, v2
	v_mov_b32_e32 v7, v18
	v_lshl_add_u64 v[8:9], v[4:5], 0, v[6:7]
	v_add_u32_e32 v7, 0x400, v17
	s_waitcnt lgkmcnt(0)
	s_barrier
	ds_read2_b32 v[24:25], v17 offset1:32
	ds_read2_b32 v[26:27], v17 offset0:65 offset1:97
	ds_read2_b32 v[28:29], v17 offset0:130 offset1:162
	ds_read2_b32 v[30:31], v17 offset0:195 offset1:227
	ds_read2_b32 v[32:33], v7 offset0:4 offset1:36
	ds_read2_b32 v[34:35], v7 offset0:69 offset1:101
	ds_read2_b32 v[36:37], v7 offset0:134 offset1:166
	ds_read2_b32 v[38:39], v7 offset0:199 offset1:231
	v_lshl_add_u64 v[40:41], v[8:9], 0, v[40:41]
	s_waitcnt lgkmcnt(6)
	v_cvt_pk_bf16_f32 v4, v24, v26
	s_waitcnt lgkmcnt(4)
	v_cvt_pk_bf16_f32 v5, v28, v30
	s_waitcnt lgkmcnt(2)
	v_cvt_pk_bf16_f32 v6, v32, v34
	s_waitcnt lgkmcnt(0)
	v_cvt_pk_bf16_f32 v7, v36, v38
	v_or_b32_e32 v24, v42, v19
	global_store_dwordx4 v[40:41], v[4:7], off
	v_mul_u32_u24_e32 v24, 0x2b00, v24
	s_nop 0
	v_cvt_pk_bf16_f32 v4, v25, v27
	v_mov_b32_e32 v25, v18
	v_cvt_pk_bf16_f32 v5, v29, v31
	v_cvt_pk_bf16_f32 v6, v33, v35
	v_cvt_pk_bf16_f32 v7, v37, v39
	v_lshl_add_u64 v[8:9], v[8:9], 0, v[24:25]
	global_store_dwordx4 v[8:9], v[4:7], off
	s_barrier

; __device__ __forceinline__ void conv_tile(const Ctx& cx, const float* __restrict__ src, bfu* __restrict__ dst, int K, int N, int kt, int nt, int perm) {
;   char* smem = cx.lds;
;   float* tile = reinterpret_cast<float*>(smem);
;   const int tid = cx.tid;
;   const int k0 = kt * 64, n0 = nt * 64;
; #pragma unroll
;   for (int i = 0; i < 4; ++i) {
;     int kk = (tid >> 4) + 16 * i, nn = (tid & 15) * 4;
;     float4 v = *reinterpret_cast<const float4*>(src + (size_t)(k0 + kk) * N + n0 + nn);
;     tile[kk * 65 + nn] = v.x; tile[kk * 65 + nn + 1] = v.y; tile[kk * 65 + nn + 2] = v.z; tile[kk * 65 + nn + 3] = v.w;
;   }
;   __syncthreads();
; #pragma unroll
;   for (int i = 0; i < 2; ++i) {
;     int q = tid + 256 * i, nn = q >> 3, kc = q & 7;
;     int j = n0 + nn, drow = j;
;     if (perm == 1) {
;       if (j < DFF) drow = (j >> 4) * 32 + (j & 15);
;       else { int jj = j - DFF; drow = (jj >> 4) * 32 + 16 + (jj & 15); }
;     } else if (perm == 2) {
;       int sec = j >> 9;
;       if (sec == 5 || sec == 6 || sec == 9 || sec == 10) {
;         int d = j & 63;
;         int pos = d < 16 ? d : (d < 32 ? d + 16 : (d < 48 ? d - 16 : d));
;         drow = (j & ~63) + pos;
;       }
;     }
;     uint4 o;
;     o.x = pack2(tile[(kc * 8 + 0) * 65 + nn], tile[(kc * 8 + 1) * 65 + nn]);
;     o.y = pack2(tile[(kc * 8 + 2) * 65 + nn], tile[(kc * 8 + 3) * 65 + nn]);
;     o.z = pack2(tile[(kc * 8 + 4) * 65 + nn], tile[(kc * 8 + 5) * 65 + nn]);
;     o.w = pack2(tile[(kc * 8 + 6) * 65 + nn], tile[(kc * 8 + 7) * 65 + nn]);
;     *reinterpret_cast<uint4*>(dst + (size_t)drow * K + k0 + kc * 8) = o;
;   }
;   __syncthreads();
; }
; __device__ __forceinline__ void conv_item(const Ctx& cx, const Params& p, int l, int r) {
;   if (r < 11008) {
;     int f = r / 5504, rr = r % 5504;
;     conv_tile(cx, p.ffn_w_in + (size_t)(l * 2 + f) * 2048 * 11008, reinterpret_cast<bfu*>(p.ws + OFF_WFIN) + (size_t)(l * 2 + f) * 11008 * 2048,
;               2048, 11008, rr / 172, rr % 172, 1);
.LBB0_946:
	s_andn2_saveexec_b64 s[0:1], s[10:11]
	s_cbranch_execz .LBB0_915
	s_mov_b32 s2, 0x2fa0be83
	v_mul_hi_i32 v6, v5, s2
	v_lshrrev_b32_e32 v7, 31, v6
	v_ashrrev_i32_e32 v6, 10, v6
	v_add_u32_e32 v6, v6, v7
	v_readlane_b32 s72, v254, 9
	v_mul_i32_i24_e32 v7, 0x1580, v6
	v_readlane_b32 s73, v254, 10
	v_sub_u32_e32 v24, v5, v7
	v_lshl_add_u32 v7, v4, 1, v6
	v_mov_b64_e32 v[4:5], s[72:73]
	s_mov_b32 s2, 0x5600000
	v_mad_i64_i32 v[8:9], s[2:3], v7, s2, v[4:5]
	v_mul_i32_i24_e32 v4, 0x2fa1, v24
	v_lshrrev_b32_e32 v5, 31, v4
	v_ashrrev_i32_e32 v4, 21, v4
	v_add_u16_e32 v4, v4, v5
	v_mul_lo_u16_e32 v5, 0xac, v4
	v_sub_u16_e32 v5, v24, v5
	v_lshlrev_b32_sdwa v6, v191, sext(v4) dst_sel:DWORD dst_unused:UNUSED_PAD src0_sel:DWORD src1_sel:WORD_0
	v_lshlrev_b32_sdwa v4, v191, sext(v5) dst_sel:DWORD dst_unused:UNUSED_PAD src0_sel:DWORD src1_sel:WORD_0
	v_ashrrev_i32_e32 v5, 31, v4
	v_lshl_add_u64 v[8:9], v[4:5], 2, v[8:9]
	v_lshlrev_b32_e32 v24, 2, v0
	v_mov_b32_e32 v25, v18
	v_or_b32_e32 v5, v6, v1
	v_lshl_add_u64 v[8:9], v[8:9], 0, v[24:25]
	v_mul_i32_i24_e32 v24, 0xac00, v5
	v_ashrrev_i32_e32 v25, 31, v24
	v_lshl_add_u64 v[24:25], v[8:9], 0, v[24:25]
	global_load_dwordx4 v[24:27], v[24:25], off nt
	v_or_b32_e32 v5, v6, v10
	v_readlane_b32 s74, v254, 11
	v_readlane_b32 s75, v254, 12
	v_readlane_b32 s76, v254, 13
	v_readlane_b32 s77, v254, 14
	v_readlane_b32 s78, v254, 15
	v_readlane_b32 s79, v254, 16
	v_readlane_b32 s80, v254, 17
	v_readlane_b32 s81, v254, 18
	v_readlane_b32 s82, v254, 19
	v_readlane_b32 s83, v254, 20
	v_readlane_b32 s84, v254, 21
	v_readlane_b32 s85, v254, 22
	v_readlane_b32 s86, v254, 23
	v_readlane_b32 s87, v254, 24
	s_waitcnt vmcnt(0)
	ds_write2_b32 v3, v24, v25 offset1:1
	ds_write2_b32 v3, v26, v27 offset0:2 offset1:3
	v_mul_i32_i24_e32 v24, 0xac00, v5
	v_ashrrev_i32_e32 v25, 31, v24
	v_lshl_add_u64 v[24:25], v[8:9], 0, v[24:25]
	global_load_dwordx4 v[24:27], v[24:25], off nt
	v_or_b32_e32 v5, v6, v12
	s_waitcnt vmcnt(0)
	ds_write2_b32 v11, v24, v25 offset1:1
	ds_write2_b32 v11, v26, v27 offset0:2 offset1:3
	v_mul_i32_i24_e32 v24, 0xac00, v5
	v_ashrrev_i32_e32 v25, 31, v24
	v_lshl_add_u64 v[24:25], v[8:9], 0, v[24:25]
	global_load_dwordx4 v[24:27], v[24:25], off nt
	v_or_b32_e32 v5, v6, v14
	s_waitcnt vmcnt(0)
	ds_write2_b32 v13, v24, v25 offset1:1
	ds_write2_b32 v13, v26, v27 offset0:2 offset1:3
	v_mul_i32_i24_e32 v24, 0xac00, v5
	v_ashrrev_i32_e32 v25, 31, v24
	v_lshl_add_u64 v[8:9], v[8:9], 0, v[24:25]
	global_load_dwordx4 v[24:27], v[8:9], off nt
	v_or_b32_e32 v5, v4, v16
	v_cmp_lt_i32_e32 vcc, s47, v5
	v_lshlrev_b32_e32 v5, 1, v5
	s_waitcnt vmcnt(0)
	ds_write2_b32 v15, v24, v25 offset1:1
	ds_write2_b32 v15, v26, v27 offset0:2 offset1:3
	s_waitcnt lgkmcnt(0)
	s_barrier
	s_and_saveexec_b64 s[2:3], vcc
	s_xor_b64 s[2:3], exec, s[2:3]
	v_add_u32_e32 v5, 0x7fffd500, v5
	s_mov_b32 s10, 0x7fffffa0
	v_and_or_b32 v8, v5, s10, v23
	s_andn2_saveexec_b64 s[2:3], s[2:3]
	s_movk_i32 s10, 0xffa0
	v_and_or_b32 v8, v5, s10, v22
	s_or_b64 exec, exec, s[2:3]
	v_mov_b64_e32 v[24:25], s[90:91]
	v_mad_i64_i32 v[24:25], s[2:3], v7, s21, v[24:25]
	v_ashrrev_i32_e32 v7, 31, v6
	v_lshl_add_u64 v[6:7], v[6:7], 1, v[24:25]
	v_lshlrev_b32_e32 v24, 1, v2
	v_mov_b32_e32 v25, v18
	v_lshl_add_u64 v[6:7], v[6:7], 0, v[24:25]
	ds_read2_b32 v[24:25], v17 offset1:65
	ds_read2_b32 v[26:27], v17 offset0:130 offset1:195
	v_add_u32_e32 v5, 0x400, v17
	ds_read2_b32 v[28:29], v5 offset0:134 offset1:199
	v_ashrrev_i32_e32 v9, 31, v8
	s_waitcnt lgkmcnt(2)
	v_cvt_pk_bf16_f32 v24, v24, v25
	s_waitcnt lgkmcnt(1)
	v_cvt_pk_bf16_f32 v25, v26, v27
	ds_read2_b32 v[26:27], v5 offset0:4 offset1:69
	v_lshlrev_b64 v[8:9], 12, v[8:9]
	v_lshl_add_u64 v[8:9], v[6:7], 0, v[8:9]
	v_or_b32_e32 v4, v4, v19
	v_cmp_lt_i32_e32 vcc, s47, v4
	s_waitcnt lgkmcnt(0)
	v_cvt_pk_bf16_f32 v26, v26, v27
	v_cvt_pk_bf16_f32 v27, v28, v29
	global_store_dwordx4 v[8:9], v[24:27], off
	v_lshlrev_b32_e32 v8, 1, v4
	s_and_saveexec_b64 s[2:3], vcc
	s_xor_b64 s[2:3], exec, s[2:3]
	v_add_u32_e32 v4, 0x7fffd500, v8
	s_mov_b32 s10, 0x7fffffe0
	v_and_or_b32 v4, v4, s10, v23
	s_andn2_saveexec_b64 s[2:3], s[2:3]
	s_cbranch_execz .LBB0_914
	s_movk_i32 s10, 0xffe0
	v_and_or_b32 v4, v8, s10, v22
	s_branch .LBB0_914
